# LRU scans S1/S2/S3: row loads of each unrolled group issued together with counted vmcnt (were waited one by one)
# speedup vs baseline: 1.1222x; 1.0434x over previous
; __device__ __forceinline__ unsigned pk2(float a, float b) { return cvtpk(a, b); }
; __device__ __forceinline__ float blo(unsigned u) { return __uint_as_float(u << 16); }
; __device__ __forceinline__ float bhi(unsigned u) { return __uint_as_float(u & 0xffff0000u); }
; __device__ __forceinline__ float siluf(float x) { return x * sigm(x); }
; __device__ __forceinline__ void ph_lru_s3(const P& p, int d) {
;     ...
;   for (int it = xcd_swz() * 8 + (t >> 6); it < 2600; it += gridDim.x * 8) {
;     int b = it / 1300, r = it % 1300, cc = r / 5, ch = (r % 5) * 256 + (t & 63) * 4;
;     float4 h = *(const float4*)(CAR + (size_t)(b * NCH_ + cc) * 1280 + ch);
; #pragma unroll 8
;     for (int q = 0; q < 64; q++) { size_t o = (size_t)rowmap(d, b, cc * 64 + q) * 1280 + ch; uint4 u = *(const uint4*)(AB + o);
;       h.x = (1.f - bhi(u.x)) * h.x + blo(u.x); h.y = (1.f - bhi(u.y)) * h.y + blo(u.y); h.z = (1.f - bhi(u.z)) * h.z + blo(u.z); h.w = (1.f - bhi(u.w)) * h.w + blo(u.w);
;       if (d == 0) *(uint2*)(HF + o) = uint2{pk2(h.x, h.y), pk2(h.z, h.w)};
;       else { uint2 hf = *(const uint2*)(HF + o), zz = *(const uint2*)(Z + o);
;         *(uint2*)(Z + o) = uint2{pk2((blo(hf.x) + h.x) * siluf(blo(zz.x)), (bhi(hf.x) + h.y) * siluf(bhi(zz.x))), pk2((blo(hf.y) + h.z) * siluf(blo(zz.y)), (bhi(hf.y) + h.w) * siluf(bhi(zz.y)))}; } }
.LBB0_1485:
	s_cmp_lg_u32 s18, 0
	s_cbranch_scc1 .Ls3_body_d1
	v_add_u32_e32 v8, -7, v12
	v_cmp_lt_i32_e32 vcc, s15, v8
	v_sub_u32_e32 v14, v176, v8
	v_sub_u32_e32 v9, v177, v8
	v_cndmask_b32_e32 v9, v14, v9, vcc
	v_cndmask_b32_e64 v8, v9, v8, s[40:41]
	v_add_u32_e32 v8, v8, v11
	v_mad_i64_i32 v[32:33], s[12:13], v8, s17, v[6:7]
	v_lshl_add_u64 v[14:15], v[32:33], 2, s[2:3]
	global_load_dwordx4 v[48:51], v[14:15], off
	v_add_u32_e32 v8, -6, v12
	v_cmp_lt_i32_e32 vcc, s15, v8
	v_sub_u32_e32 v14, v176, v8
	v_sub_u32_e32 v9, v177, v8
	v_cndmask_b32_e32 v9, v14, v9, vcc
	v_cndmask_b32_e64 v8, v9, v8, s[40:41]
	v_add_u32_e32 v8, v8, v11
	v_mad_i64_i32 v[34:35], s[12:13], v8, s17, v[6:7]
	v_lshl_add_u64 v[14:15], v[34:35], 2, s[2:3]
	global_load_dwordx4 v[52:55], v[14:15], off
	v_add_u32_e32 v8, -5, v12
	v_cmp_lt_i32_e32 vcc, s15, v8
	v_sub_u32_e32 v14, v176, v8
	v_sub_u32_e32 v9, v177, v8
	v_cndmask_b32_e32 v9, v14, v9, vcc
	v_cndmask_b32_e64 v8, v9, v8, s[40:41]
	v_add_u32_e32 v8, v8, v11
	v_mad_i64_i32 v[36:37], s[12:13], v8, s17, v[6:7]
	v_lshl_add_u64 v[14:15], v[36:37], 2, s[2:3]
	global_load_dwordx4 v[56:59], v[14:15], off
	v_add_u32_e32 v8, -4, v12
	v_cmp_lt_i32_e32 vcc, s15, v8
	v_sub_u32_e32 v14, v176, v8
	v_sub_u32_e32 v9, v177, v8
	v_cndmask_b32_e32 v9, v14, v9, vcc
	v_cndmask_b32_e64 v8, v9, v8, s[40:41]
	v_add_u32_e32 v8, v8, v11
	v_mad_i64_i32 v[38:39], s[12:13], v8, s17, v[6:7]
	v_lshl_add_u64 v[14:15], v[38:39], 2, s[2:3]
	global_load_dwordx4 v[60:63], v[14:15], off
	v_add_u32_e32 v8, -3, v12
	v_cmp_lt_i32_e32 vcc, s15, v8
	v_sub_u32_e32 v14, v176, v8
	v_sub_u32_e32 v9, v177, v8
	v_cndmask_b32_e32 v9, v14, v9, vcc
	v_cndmask_b32_e64 v8, v9, v8, s[40:41]
	v_add_u32_e32 v8, v8, v11
	v_mad_i64_i32 v[40:41], s[12:13], v8, s17, v[6:7]
	v_lshl_add_u64 v[14:15], v[40:41], 2, s[2:3]
	global_load_dwordx4 v[64:67], v[14:15], off
	v_add_u32_e32 v8, -2, v12
	v_cmp_lt_i32_e32 vcc, s15, v8
	v_sub_u32_e32 v14, v176, v8
	v_sub_u32_e32 v9, v177, v8
	v_cndmask_b32_e32 v9, v14, v9, vcc
	v_cndmask_b32_e64 v8, v9, v8, s[40:41]
	v_add_u32_e32 v8, v8, v11
	v_mad_i64_i32 v[42:43], s[12:13], v8, s17, v[6:7]
	v_lshl_add_u64 v[14:15], v[42:43], 2, s[2:3]
	global_load_dwordx4 v[68:71], v[14:15], off
	v_add_u32_e32 v8, -1, v12
	v_cmp_lt_i32_e32 vcc, s15, v8
	v_sub_u32_e32 v14, v176, v8
	v_sub_u32_e32 v9, v177, v8
	v_cndmask_b32_e32 v9, v14, v9, vcc
	v_cndmask_b32_e64 v8, v9, v8, s[40:41]
	v_add_u32_e32 v8, v8, v11
	v_mad_i64_i32 v[44:45], s[12:13], v8, s17, v[6:7]
	v_lshl_add_u64 v[14:15], v[44:45], 2, s[2:3]
	global_load_dwordx4 v[72:75], v[14:15], off
	v_mov_b32_e32 v8, v12
	v_cmp_lt_i32_e32 vcc, s15, v8
	v_sub_u32_e32 v14, v176, v8
	v_sub_u32_e32 v9, v177, v8
	v_cndmask_b32_e32 v9, v14, v9, vcc
	v_cndmask_b32_e64 v8, v9, v8, s[40:41]
	v_add_u32_e32 v8, v8, v11
	v_mad_i64_i32 v[46:47], s[12:13], v8, s17, v[6:7]
	v_lshl_add_u64 v[14:15], v[46:47], 2, s[2:3]
	global_load_dwordx4 v[76:79], v[14:15], off
	s_waitcnt vmcnt(7)
	v_and_b32_e32 v19, 0xffff0000, v49
	v_and_b32_e32 v18, 0xffff0000, v48
	v_pk_add_f32 v[18:19], v[18:19], 1.0 op_sel_hi:[1,0] neg_lo:[1,0] neg_hi:[1,0]
	v_lshlrev_b32_e32 v49, 16, v49
	v_lshlrev_b32_e32 v48, 16, v48
	v_pk_fma_f32 v[2:3], v[2:3], v[18:19], v[48:49]
	v_and_b32_e32 v19, 0xffff0000, v51
	v_and_b32_e32 v18, 0xffff0000, v50
	v_pk_add_f32 v[18:19], v[18:19], 1.0 op_sel_hi:[1,0] neg_lo:[1,0] neg_hi:[1,0]
	v_lshlrev_b32_e32 v51, 16, v51
	v_lshlrev_b32_e32 v50, 16, v50
	v_pk_fma_f32 v[4:5], v[4:5], v[18:19], v[50:51]
	v_cvt_pk_bf16_f32 v14, v2, v3
	v_cvt_pk_bf16_f32 v15, v4, v5
	v_lshl_add_u64 v[32:33], v[32:33], 1, s[36:37]
	global_store_dwordx2 v[32:33], v[14:15], off
	s_waitcnt vmcnt(7)
	v_and_b32_e32 v19, 0xffff0000, v53
	v_and_b32_e32 v18, 0xffff0000, v52
	v_pk_add_f32 v[18:19], v[18:19], 1.0 op_sel_hi:[1,0] neg_lo:[1,0] neg_hi:[1,0]
	v_lshlrev_b32_e32 v53, 16, v53
	v_lshlrev_b32_e32 v52, 16, v52
	v_pk_fma_f32 v[2:3], v[2:3], v[18:19], v[52:53]
	v_and_b32_e32 v19, 0xffff0000, v55
	v_and_b32_e32 v18, 0xffff0000, v54
	v_pk_add_f32 v[18:19], v[18:19], 1.0 op_sel_hi:[1,0] neg_lo:[1,0] neg_hi:[1,0]
	v_lshlrev_b32_e32 v55, 16, v55
	v_lshlrev_b32_e32 v54, 16, v54
	v_pk_fma_f32 v[4:5], v[4:5], v[18:19], v[54:55]
	v_cvt_pk_bf16_f32 v24, v2, v3
	v_cvt_pk_bf16_f32 v25, v4, v5
	v_lshl_add_u64 v[34:35], v[34:35], 1, s[36:37]
	global_store_dwordx2 v[34:35], v[24:25], off
	s_waitcnt vmcnt(7)
	v_and_b32_e32 v19, 0xffff0000, v57
	v_and_b32_e32 v18, 0xffff0000, v56
	v_pk_add_f32 v[18:19], v[18:19], 1.0 op_sel_hi:[1,0] neg_lo:[1,0] neg_hi:[1,0]
	v_lshlrev_b32_e32 v57, 16, v57
	v_lshlrev_b32_e32 v56, 16, v56
	v_pk_fma_f32 v[2:3], v[2:3], v[18:19], v[56:57]
	v_and_b32_e32 v19, 0xffff0000, v59
	v_and_b32_e32 v18, 0xffff0000, v58
	v_pk_add_f32 v[18:19], v[18:19], 1.0 op_sel_hi:[1,0] neg_lo:[1,0] neg_hi:[1,0]
	v_lshlrev_b32_e32 v59, 16, v59
	v_lshlrev_b32_e32 v58, 16, v58
	v_pk_fma_f32 v[4:5], v[4:5], v[18:19], v[58:59]
	v_cvt_pk_bf16_f32 v14, v2, v3
	v_cvt_pk_bf16_f32 v15, v4, v5
	v_lshl_add_u64 v[36:37], v[36:37], 1, s[36:37]
	global_store_dwordx2 v[36:37], v[14:15], off
	s_waitcnt vmcnt(7)
	v_and_b32_e32 v19, 0xffff0000, v61
	v_and_b32_e32 v18, 0xffff0000, v60
	v_pk_add_f32 v[18:19], v[18:19], 1.0 op_sel_hi:[1,0] neg_lo:[1,0] neg_hi:[1,0]
	v_lshlrev_b32_e32 v61, 16, v61
	v_lshlrev_b32_e32 v60, 16, v60
	v_pk_fma_f32 v[2:3], v[2:3], v[18:19], v[60:61]
	v_and_b32_e32 v19, 0xffff0000, v63
	v_and_b32_e32 v18, 0xffff0000, v62
	v_pk_add_f32 v[18:19], v[18:19], 1.0 op_sel_hi:[1,0] neg_lo:[1,0] neg_hi:[1,0]
	v_lshlrev_b32_e32 v63, 16, v63
	v_lshlrev_b32_e32 v62, 16, v62
	v_pk_fma_f32 v[4:5], v[4:5], v[18:19], v[62:63]
	v_cvt_pk_bf16_f32 v24, v2, v3
	v_cvt_pk_bf16_f32 v25, v4, v5
	v_lshl_add_u64 v[38:39], v[38:39], 1, s[36:37]
	global_store_dwordx2 v[38:39], v[24:25], off
	s_waitcnt vmcnt(7)
; __device__ __forceinline__ unsigned pk2(float a, float b) { return cvtpk(a, b); }
; __device__ __forceinline__ float blo(unsigned u) { return __uint_as_float(u << 16); }
; __device__ __forceinline__ float bhi(unsigned u) { return __uint_as_float(u & 0xffff0000u); }
; __device__ __forceinline__ float siluf(float x) { return x * sigm(x); }
; __device__ __forceinline__ void ph_lru_s3(const P& p, int d) {
;     ...
;   for (int it = xcd_swz() * 8 + (t >> 6); it < 2600; it += gridDim.x * 8) {
;     int b = it / 1300, r = it % 1300, cc = r / 5, ch = (r % 5) * 256 + (t & 63) * 4;
;     float4 h = *(const float4*)(CAR + (size_t)(b * NCH_ + cc) * 1280 + ch);
; #pragma unroll 8
;     for (int q = 0; q < 64; q++) { size_t o = (size_t)rowmap(d, b, cc * 64 + q) * 1280 + ch; uint4 u = *(const uint4*)(AB + o);
;       h.x = (1.f - bhi(u.x)) * h.x + blo(u.x); h.y = (1.f - bhi(u.y)) * h.y + blo(u.y); h.z = (1.f - bhi(u.z)) * h.z + blo(u.z); h.w = (1.f - bhi(u.w)) * h.w + blo(u.w);
;       if (d == 0) *(uint2*)(HF + o) = uint2{pk2(h.x, h.y), pk2(h.z, h.w)};
;       else { uint2 hf = *(const uint2*)(HF + o), zz = *(const uint2*)(Z + o);
;         *(uint2*)(Z + o) = uint2{pk2((blo(hf.x) + h.x) * siluf(blo(zz.x)), (bhi(hf.x) + h.y) * siluf(bhi(zz.x))), pk2((blo(hf.y) + h.z) * siluf(blo(zz.y)), (bhi(hf.y) + h.w) * siluf(bhi(zz.y)))}; } }
	v_and_b32_e32 v19, 0xffff0000, v65
	v_and_b32_e32 v18, 0xffff0000, v64
	v_pk_add_f32 v[18:19], v[18:19], 1.0 op_sel_hi:[1,0] neg_lo:[1,0] neg_hi:[1,0]
	v_lshlrev_b32_e32 v65, 16, v65
	v_lshlrev_b32_e32 v64, 16, v64
	v_pk_fma_f32 v[2:3], v[2:3], v[18:19], v[64:65]
	v_and_b32_e32 v19, 0xffff0000, v67
	v_and_b32_e32 v18, 0xffff0000, v66
	v_pk_add_f32 v[18:19], v[18:19], 1.0 op_sel_hi:[1,0] neg_lo:[1,0] neg_hi:[1,0]
	v_lshlrev_b32_e32 v67, 16, v67
	v_lshlrev_b32_e32 v66, 16, v66
	v_pk_fma_f32 v[4:5], v[4:5], v[18:19], v[66:67]
	v_cvt_pk_bf16_f32 v14, v2, v3
	v_cvt_pk_bf16_f32 v15, v4, v5
	v_lshl_add_u64 v[40:41], v[40:41], 1, s[36:37]
	global_store_dwordx2 v[40:41], v[14:15], off
	s_waitcnt vmcnt(7)
	v_and_b32_e32 v19, 0xffff0000, v69
	v_and_b32_e32 v18, 0xffff0000, v68
	v_pk_add_f32 v[18:19], v[18:19], 1.0 op_sel_hi:[1,0] neg_lo:[1,0] neg_hi:[1,0]
	v_lshlrev_b32_e32 v69, 16, v69
	v_lshlrev_b32_e32 v68, 16, v68
	v_pk_fma_f32 v[2:3], v[2:3], v[18:19], v[68:69]
	v_and_b32_e32 v19, 0xffff0000, v71
	v_and_b32_e32 v18, 0xffff0000, v70
	v_pk_add_f32 v[18:19], v[18:19], 1.0 op_sel_hi:[1,0] neg_lo:[1,0] neg_hi:[1,0]
	v_lshlrev_b32_e32 v71, 16, v71
	v_lshlrev_b32_e32 v70, 16, v70
	v_pk_fma_f32 v[4:5], v[4:5], v[18:19], v[70:71]
	v_cvt_pk_bf16_f32 v24, v2, v3
	v_cvt_pk_bf16_f32 v25, v4, v5
	v_lshl_add_u64 v[42:43], v[42:43], 1, s[36:37]
	global_store_dwordx2 v[42:43], v[24:25], off
	s_waitcnt vmcnt(7)
	v_and_b32_e32 v19, 0xffff0000, v73
	v_and_b32_e32 v18, 0xffff0000, v72
	v_pk_add_f32 v[18:19], v[18:19], 1.0 op_sel_hi:[1,0] neg_lo:[1,0] neg_hi:[1,0]
	v_lshlrev_b32_e32 v73, 16, v73
	v_lshlrev_b32_e32 v72, 16, v72
	v_pk_fma_f32 v[2:3], v[2:3], v[18:19], v[72:73]
	v_and_b32_e32 v19, 0xffff0000, v75
	v_and_b32_e32 v18, 0xffff0000, v74
	v_pk_add_f32 v[18:19], v[18:19], 1.0 op_sel_hi:[1,0] neg_lo:[1,0] neg_hi:[1,0]
	v_lshlrev_b32_e32 v75, 16, v75
	v_lshlrev_b32_e32 v74, 16, v74
	v_pk_fma_f32 v[4:5], v[4:5], v[18:19], v[74:75]
	v_cvt_pk_bf16_f32 v14, v2, v3
	v_cvt_pk_bf16_f32 v15, v4, v5
	v_lshl_add_u64 v[44:45], v[44:45], 1, s[36:37]
	global_store_dwordx2 v[44:45], v[14:15], off
	s_waitcnt vmcnt(7)
	v_and_b32_e32 v19, 0xffff0000, v77
	v_and_b32_e32 v18, 0xffff0000, v76
	v_pk_add_f32 v[18:19], v[18:19], 1.0 op_sel_hi:[1,0] neg_lo:[1,0] neg_hi:[1,0]
	v_lshlrev_b32_e32 v77, 16, v77
	v_lshlrev_b32_e32 v76, 16, v76
	v_pk_fma_f32 v[2:3], v[2:3], v[18:19], v[76:77]
	v_and_b32_e32 v19, 0xffff0000, v79
	v_and_b32_e32 v18, 0xffff0000, v78
	v_pk_add_f32 v[18:19], v[18:19], 1.0 op_sel_hi:[1,0] neg_lo:[1,0] neg_hi:[1,0]
	v_lshlrev_b32_e32 v79, 16, v79
	v_lshlrev_b32_e32 v78, 16, v78
	v_pk_fma_f32 v[4:5], v[4:5], v[18:19], v[78:79]
	v_cvt_pk_bf16_f32 v24, v2, v3
	v_cvt_pk_bf16_f32 v25, v4, v5
	v_lshl_add_u64 v[46:47], v[46:47], 1, s[36:37]
	global_store_dwordx2 v[46:47], v[24:25], off
	s_branch .LBB0_1484
.Ls3_body_d1:
	v_add_u32_e32 v8, -7, v12
	v_cmp_lt_i32_e32 vcc, s15, v8
	v_sub_u32_e32 v14, v176, v8
	v_sub_u32_e32 v9, v177, v8
	v_cndmask_b32_e32 v9, v14, v9, vcc
	v_cndmask_b32_e64 v8, v9, v8, s[40:41]
	v_add_u32_e32 v8, v8, v11
	v_mad_i64_i32 v[32:33], s[12:13], v8, s17, v[6:7]
	v_lshl_add_u64 v[14:15], v[32:33], 2, s[2:3]
	global_load_dwordx4 v[48:51], v[14:15], off
	v_lshl_add_u64 v[16:17], v[32:33], 1, s[36:37]
	v_lshl_add_u64 v[32:33], v[32:33], 1, s[26:27]
	global_load_dwordx2 v[80:81], v[16:17], off
	global_load_dwordx2 v[96:97], v[32:33], off
	v_add_u32_e32 v8, -6, v12
	v_cmp_lt_i32_e32 vcc, s15, v8
	v_sub_u32_e32 v14, v176, v8
	v_sub_u32_e32 v9, v177, v8
	v_cndmask_b32_e32 v9, v14, v9, vcc
	v_cndmask_b32_e64 v8, v9, v8, s[40:41]
	v_add_u32_e32 v8, v8, v11
	v_mad_i64_i32 v[34:35], s[12:13], v8, s17, v[6:7]
	v_lshl_add_u64 v[14:15], v[34:35], 2, s[2:3]
	global_load_dwordx4 v[52:55], v[14:15], off
	v_lshl_add_u64 v[16:17], v[34:35], 1, s[36:37]
	v_lshl_add_u64 v[34:35], v[34:35], 1, s[26:27]
	global_load_dwordx2 v[82:83], v[16:17], off
	global_load_dwordx2 v[98:99], v[34:35], off
	v_add_u32_e32 v8, -5, v12
	v_cmp_lt_i32_e32 vcc, s15, v8
	v_sub_u32_e32 v14, v176, v8
	v_sub_u32_e32 v9, v177, v8
	v_cndmask_b32_e32 v9, v14, v9, vcc
	v_cndmask_b32_e64 v8, v9, v8, s[40:41]
	v_add_u32_e32 v8, v8, v11
	v_mad_i64_i32 v[36:37], s[12:13], v8, s17, v[6:7]
	v_lshl_add_u64 v[14:15], v[36:37], 2, s[2:3]
	global_load_dwordx4 v[56:59], v[14:15], off
	v_lshl_add_u64 v[16:17], v[36:37], 1, s[36:37]
	v_lshl_add_u64 v[36:37], v[36:37], 1, s[26:27]
	global_load_dwordx2 v[84:85], v[16:17], off
	global_load_dwordx2 v[100:101], v[36:37], off
	v_add_u32_e32 v8, -4, v12
	v_cmp_lt_i32_e32 vcc, s15, v8
	v_sub_u32_e32 v14, v176, v8
	v_sub_u32_e32 v9, v177, v8
	v_cndmask_b32_e32 v9, v14, v9, vcc
	v_cndmask_b32_e64 v8, v9, v8, s[40:41]
	v_add_u32_e32 v8, v8, v11
	v_mad_i64_i32 v[38:39], s[12:13], v8, s17, v[6:7]
	v_lshl_add_u64 v[14:15], v[38:39], 2, s[2:3]
	global_load_dwordx4 v[60:63], v[14:15], off
	v_lshl_add_u64 v[16:17], v[38:39], 1, s[36:37]
	v_lshl_add_u64 v[38:39], v[38:39], 1, s[26:27]
	global_load_dwordx2 v[86:87], v[16:17], off
	global_load_dwordx2 v[102:103], v[38:39], off
	v_add_u32_e32 v8, -3, v12
	v_cmp_lt_i32_e32 vcc, s15, v8
	v_sub_u32_e32 v14, v176, v8
	v_sub_u32_e32 v9, v177, v8
	v_cndmask_b32_e32 v9, v14, v9, vcc
	v_cndmask_b32_e64 v8, v9, v8, s[40:41]
	v_add_u32_e32 v8, v8, v11
	v_mad_i64_i32 v[40:41], s[12:13], v8, s17, v[6:7]
	v_lshl_add_u64 v[14:15], v[40:41], 2, s[2:3]
	global_load_dwordx4 v[64:67], v[14:15], off
	v_lshl_add_u64 v[16:17], v[40:41], 1, s[36:37]
	v_lshl_add_u64 v[40:41], v[40:41], 1, s[26:27]
	global_load_dwordx2 v[88:89], v[16:17], off
	global_load_dwordx2 v[104:105], v[40:41], off
	v_add_u32_e32 v8, -2, v12
	v_cmp_lt_i32_e32 vcc, s15, v8
; __device__ __forceinline__ unsigned pk2(float a, float b) { return cvtpk(a, b); }
; __device__ __forceinline__ float blo(unsigned u) { return __uint_as_float(u << 16); }
; __device__ __forceinline__ float bhi(unsigned u) { return __uint_as_float(u & 0xffff0000u); }
; __device__ __forceinline__ float siluf(float x) { return x * sigm(x); }
; __device__ __forceinline__ void ph_lru_s3(const P& p, int d) {
;     ...
;   for (int it = xcd_swz() * 8 + (t >> 6); it < 2600; it += gridDim.x * 8) {
;     int b = it / 1300, r = it % 1300, cc = r / 5, ch = (r % 5) * 256 + (t & 63) * 4;
;     float4 h = *(const float4*)(CAR + (size_t)(b * NCH_ + cc) * 1280 + ch);
; #pragma unroll 8
;     for (int q = 0; q < 64; q++) { size_t o = (size_t)rowmap(d, b, cc * 64 + q) * 1280 + ch; uint4 u = *(const uint4*)(AB + o);
;       h.x = (1.f - bhi(u.x)) * h.x + blo(u.x); h.y = (1.f - bhi(u.y)) * h.y + blo(u.y); h.z = (1.f - bhi(u.z)) * h.z + blo(u.z); h.w = (1.f - bhi(u.w)) * h.w + blo(u.w);
;       if (d == 0) *(uint2*)(HF + o) = uint2{pk2(h.x, h.y), pk2(h.z, h.w)};
;       else { uint2 hf = *(const uint2*)(HF + o), zz = *(const uint2*)(Z + o);
;         *(uint2*)(Z + o) = uint2{pk2((blo(hf.x) + h.x) * siluf(blo(zz.x)), (bhi(hf.x) + h.y) * siluf(bhi(zz.x))), pk2((blo(hf.y) + h.z) * siluf(blo(zz.y)), (bhi(hf.y) + h.w) * siluf(bhi(zz.y)))}; } }
	v_sub_u32_e32 v14, v176, v8
	v_sub_u32_e32 v9, v177, v8
	v_cndmask_b32_e32 v9, v14, v9, vcc
	v_cndmask_b32_e64 v8, v9, v8, s[40:41]
	v_add_u32_e32 v8, v8, v11
	v_mad_i64_i32 v[42:43], s[12:13], v8, s17, v[6:7]
	v_lshl_add_u64 v[14:15], v[42:43], 2, s[2:3]
	global_load_dwordx4 v[68:71], v[14:15], off
	v_lshl_add_u64 v[16:17], v[42:43], 1, s[36:37]
	v_lshl_add_u64 v[42:43], v[42:43], 1, s[26:27]
	global_load_dwordx2 v[90:91], v[16:17], off
	global_load_dwordx2 v[106:107], v[42:43], off
	v_add_u32_e32 v8, -1, v12
	v_cmp_lt_i32_e32 vcc, s15, v8
	v_sub_u32_e32 v14, v176, v8
	v_sub_u32_e32 v9, v177, v8
	v_cndmask_b32_e32 v9, v14, v9, vcc
	v_cndmask_b32_e64 v8, v9, v8, s[40:41]
	v_add_u32_e32 v8, v8, v11
	v_mad_i64_i32 v[44:45], s[12:13], v8, s17, v[6:7]
	v_lshl_add_u64 v[14:15], v[44:45], 2, s[2:3]
	global_load_dwordx4 v[72:75], v[14:15], off
	v_lshl_add_u64 v[16:17], v[44:45], 1, s[36:37]
	v_lshl_add_u64 v[44:45], v[44:45], 1, s[26:27]
	global_load_dwordx2 v[92:93], v[16:17], off
	global_load_dwordx2 v[108:109], v[44:45], off
	v_mov_b32_e32 v8, v12
	v_cmp_lt_i32_e32 vcc, s15, v8
	v_sub_u32_e32 v14, v176, v8
	v_sub_u32_e32 v9, v177, v8
	v_cndmask_b32_e32 v9, v14, v9, vcc
	v_cndmask_b32_e64 v8, v9, v8, s[40:41]
	v_add_u32_e32 v8, v8, v11
	v_mad_i64_i32 v[46:47], s[12:13], v8, s17, v[6:7]
	v_lshl_add_u64 v[14:15], v[46:47], 2, s[2:3]
	global_load_dwordx4 v[76:79], v[14:15], off
	v_lshl_add_u64 v[16:17], v[46:47], 1, s[36:37]
	v_lshl_add_u64 v[46:47], v[46:47], 1, s[26:27]
	global_load_dwordx2 v[94:95], v[16:17], off
	global_load_dwordx2 v[110:111], v[46:47], off
	s_waitcnt vmcnt(21)
	v_and_b32_e32 v19, 0xffff0000, v49
	v_and_b32_e32 v18, 0xffff0000, v48
	v_pk_add_f32 v[18:19], v[18:19], 1.0 op_sel_hi:[1,0] neg_lo:[1,0] neg_hi:[1,0]
	v_lshlrev_b32_e32 v49, 16, v49
	v_lshlrev_b32_e32 v48, 16, v48
	v_pk_fma_f32 v[2:3], v[2:3], v[18:19], v[48:49]
	v_and_b32_e32 v19, 0xffff0000, v51
	v_and_b32_e32 v18, 0xffff0000, v50
	v_pk_add_f32 v[18:19], v[18:19], 1.0 op_sel_hi:[1,0] neg_lo:[1,0] neg_hi:[1,0]
	v_lshlrev_b32_e32 v51, 16, v51
	v_lshlrev_b32_e32 v50, 16, v50
	v_pk_fma_f32 v[4:5], v[4:5], v[18:19], v[50:51]
	v_lshlrev_b32_e32 v20, 16, v80
	v_and_b32_e32 v21, 0xffff0000, v80
	v_lshlrev_b32_e32 v22, 16, v96
	v_mul_f32_e32 v16, 0xbfb8aa3b, v22
	v_exp_f32_e32 v16, v16
	v_and_b32_e32 v23, 0xffff0000, v96
	v_pk_add_f32 v[20:21], v[2:3], v[20:21]
	v_lshlrev_b32_e32 v18, 16, v97
	v_add_f32_e32 v16, 1.0, v16
	v_rcp_f32_e32 v24, v16
	v_mul_f32_e32 v16, 0xbfb8aa3b, v23
	v_exp_f32_e32 v16, v16
	v_and_b32_e32 v19, 0xffff0000, v97
	v_add_f32_e32 v16, 1.0, v16
	v_rcp_f32_e32 v25, v16
	s_nop 0
	v_pk_mul_f32 v[22:23], v[24:25], v[22:23]
	s_nop 0
	v_pk_mul_f32 v[20:21], v[20:21], v[22:23]
	s_nop 0
	v_cvt_pk_bf16_f32 v16, v20, v21
	v_lshlrev_b32_e32 v20, 16, v81
	v_and_b32_e32 v21, 0xffff0000, v81
	v_mul_f32_e32 v17, 0xbfb8aa3b, v18
	v_exp_f32_e32 v17, v17
	v_pk_add_f32 v[20:21], v[4:5], v[20:21]
	v_add_f32_e32 v17, 1.0, v17
	v_rcp_f32_e32 v22, v17
	v_mul_f32_e32 v17, 0xbfb8aa3b, v19
	v_exp_f32_e32 v17, v17
	s_nop 0
	v_add_f32_e32 v17, 1.0, v17
	v_rcp_f32_e32 v23, v17
	s_nop 0
	v_pk_mul_f32 v[18:19], v[22:23], v[18:19]
	s_nop 0
	v_pk_mul_f32 v[18:19], v[20:21], v[18:19]
	s_nop 0
	v_cvt_pk_bf16_f32 v17, v18, v19
	global_store_dwordx2 v[32:33], v[16:17], off
	s_waitcnt vmcnt(19)
	v_and_b32_e32 v19, 0xffff0000, v53
	v_and_b32_e32 v18, 0xffff0000, v52
	v_pk_add_f32 v[18:19], v[18:19], 1.0 op_sel_hi:[1,0] neg_lo:[1,0] neg_hi:[1,0]
	v_lshlrev_b32_e32 v53, 16, v53
	v_lshlrev_b32_e32 v52, 16, v52
	v_pk_fma_f32 v[2:3], v[2:3], v[18:19], v[52:53]
	v_and_b32_e32 v19, 0xffff0000, v55
	v_and_b32_e32 v18, 0xffff0000, v54
	v_pk_add_f32 v[18:19], v[18:19], 1.0 op_sel_hi:[1,0] neg_lo:[1,0] neg_hi:[1,0]
	v_lshlrev_b32_e32 v55, 16, v55
	v_lshlrev_b32_e32 v54, 16, v54
	v_pk_fma_f32 v[4:5], v[4:5], v[18:19], v[54:55]
	v_lshlrev_b32_e32 v20, 16, v82
	v_and_b32_e32 v21, 0xffff0000, v82
	v_lshlrev_b32_e32 v22, 16, v98
	v_mul_f32_e32 v16, 0xbfb8aa3b, v22
	v_exp_f32_e32 v16, v16
	v_and_b32_e32 v23, 0xffff0000, v98
	v_pk_add_f32 v[20:21], v[2:3], v[20:21]
	v_lshlrev_b32_e32 v18, 16, v99
	v_add_f32_e32 v16, 1.0, v16
	v_rcp_f32_e32 v24, v16
	v_mul_f32_e32 v16, 0xbfb8aa3b, v23
	v_exp_f32_e32 v16, v16
	v_and_b32_e32 v19, 0xffff0000, v99
	v_add_f32_e32 v16, 1.0, v16
	v_rcp_f32_e32 v25, v16
	s_nop 0
	v_pk_mul_f32 v[22:23], v[24:25], v[22:23]
	s_nop 0
	v_pk_mul_f32 v[20:21], v[20:21], v[22:23]
	s_nop 0
	v_cvt_pk_bf16_f32 v16, v20, v21
	v_lshlrev_b32_e32 v20, 16, v83
	v_and_b32_e32 v21, 0xffff0000, v83
	v_mul_f32_e32 v17, 0xbfb8aa3b, v18
	v_exp_f32_e32 v17, v17
	v_pk_add_f32 v[20:21], v[4:5], v[20:21]
	v_add_f32_e32 v17, 1.0, v17
	v_rcp_f32_e32 v22, v17
	v_mul_f32_e32 v17, 0xbfb8aa3b, v19
	v_exp_f32_e32 v17, v17
	s_nop 0
	v_add_f32_e32 v17, 1.0, v17
	v_rcp_f32_e32 v23, v17
	s_nop 0
	v_pk_mul_f32 v[18:19], v[22:23], v[18:19]
	s_nop 0
	v_pk_mul_f32 v[18:19], v[20:21], v[18:19]
	s_nop 0
	v_cvt_pk_bf16_f32 v17, v18, v19
	global_store_dwordx2 v[34:35], v[16:17], off
	s_waitcnt vmcnt(17)
; __device__ __forceinline__ unsigned pk2(float a, float b) { return cvtpk(a, b); }
; __device__ __forceinline__ float blo(unsigned u) { return __uint_as_float(u << 16); }
; __device__ __forceinline__ float bhi(unsigned u) { return __uint_as_float(u & 0xffff0000u); }
; __device__ __forceinline__ float siluf(float x) { return x * sigm(x); }
; __device__ __forceinline__ void ph_lru_s3(const P& p, int d) {
;     ...
;   for (int it = xcd_swz() * 8 + (t >> 6); it < 2600; it += gridDim.x * 8) {
;     int b = it / 1300, r = it % 1300, cc = r / 5, ch = (r % 5) * 256 + (t & 63) * 4;
;     float4 h = *(const float4*)(CAR + (size_t)(b * NCH_ + cc) * 1280 + ch);
; #pragma unroll 8
;     for (int q = 0; q < 64; q++) { size_t o = (size_t)rowmap(d, b, cc * 64 + q) * 1280 + ch; uint4 u = *(const uint4*)(AB + o);
;       h.x = (1.f - bhi(u.x)) * h.x + blo(u.x); h.y = (1.f - bhi(u.y)) * h.y + blo(u.y); h.z = (1.f - bhi(u.z)) * h.z + blo(u.z); h.w = (1.f - bhi(u.w)) * h.w + blo(u.w);
;       if (d == 0) *(uint2*)(HF + o) = uint2{pk2(h.x, h.y), pk2(h.z, h.w)};
;       else { uint2 hf = *(const uint2*)(HF + o), zz = *(const uint2*)(Z + o);
;         *(uint2*)(Z + o) = uint2{pk2((blo(hf.x) + h.x) * siluf(blo(zz.x)), (bhi(hf.x) + h.y) * siluf(bhi(zz.x))), pk2((blo(hf.y) + h.z) * siluf(blo(zz.y)), (bhi(hf.y) + h.w) * siluf(bhi(zz.y)))}; } }
	v_and_b32_e32 v19, 0xffff0000, v57
	v_and_b32_e32 v18, 0xffff0000, v56
	v_pk_add_f32 v[18:19], v[18:19], 1.0 op_sel_hi:[1,0] neg_lo:[1,0] neg_hi:[1,0]
	v_lshlrev_b32_e32 v57, 16, v57
	v_lshlrev_b32_e32 v56, 16, v56
	v_pk_fma_f32 v[2:3], v[2:3], v[18:19], v[56:57]
	v_and_b32_e32 v19, 0xffff0000, v59
	v_and_b32_e32 v18, 0xffff0000, v58
	v_pk_add_f32 v[18:19], v[18:19], 1.0 op_sel_hi:[1,0] neg_lo:[1,0] neg_hi:[1,0]
	v_lshlrev_b32_e32 v59, 16, v59
	v_lshlrev_b32_e32 v58, 16, v58
	v_pk_fma_f32 v[4:5], v[4:5], v[18:19], v[58:59]
	v_lshlrev_b32_e32 v20, 16, v84
	v_and_b32_e32 v21, 0xffff0000, v84
	v_lshlrev_b32_e32 v22, 16, v100
	v_mul_f32_e32 v16, 0xbfb8aa3b, v22
	v_exp_f32_e32 v16, v16
	v_and_b32_e32 v23, 0xffff0000, v100
	v_pk_add_f32 v[20:21], v[2:3], v[20:21]
	v_lshlrev_b32_e32 v18, 16, v101
	v_add_f32_e32 v16, 1.0, v16
	v_rcp_f32_e32 v24, v16
	v_mul_f32_e32 v16, 0xbfb8aa3b, v23
	v_exp_f32_e32 v16, v16
	v_and_b32_e32 v19, 0xffff0000, v101
	v_add_f32_e32 v16, 1.0, v16
	v_rcp_f32_e32 v25, v16
	s_nop 0
	v_pk_mul_f32 v[22:23], v[24:25], v[22:23]
	s_nop 0
	v_pk_mul_f32 v[20:21], v[20:21], v[22:23]
	s_nop 0
	v_cvt_pk_bf16_f32 v16, v20, v21
	v_lshlrev_b32_e32 v20, 16, v85
	v_and_b32_e32 v21, 0xffff0000, v85
	v_mul_f32_e32 v17, 0xbfb8aa3b, v18
	v_exp_f32_e32 v17, v17
	v_pk_add_f32 v[20:21], v[4:5], v[20:21]
	v_add_f32_e32 v17, 1.0, v17
	v_rcp_f32_e32 v22, v17
	v_mul_f32_e32 v17, 0xbfb8aa3b, v19
	v_exp_f32_e32 v17, v17
	s_nop 0
	v_add_f32_e32 v17, 1.0, v17
	v_rcp_f32_e32 v23, v17
	s_nop 0
	v_pk_mul_f32 v[18:19], v[22:23], v[18:19]
	s_nop 0
	v_pk_mul_f32 v[18:19], v[20:21], v[18:19]
	s_nop 0
	v_cvt_pk_bf16_f32 v17, v18, v19
	global_store_dwordx2 v[36:37], v[16:17], off
	s_waitcnt vmcnt(15)
	v_and_b32_e32 v19, 0xffff0000, v61
	v_and_b32_e32 v18, 0xffff0000, v60
	v_pk_add_f32 v[18:19], v[18:19], 1.0 op_sel_hi:[1,0] neg_lo:[1,0] neg_hi:[1,0]
	v_lshlrev_b32_e32 v61, 16, v61
	v_lshlrev_b32_e32 v60, 16, v60
	v_pk_fma_f32 v[2:3], v[2:3], v[18:19], v[60:61]
	v_and_b32_e32 v19, 0xffff0000, v63
	v_and_b32_e32 v18, 0xffff0000, v62
	v_pk_add_f32 v[18:19], v[18:19], 1.0 op_sel_hi:[1,0] neg_lo:[1,0] neg_hi:[1,0]
	v_lshlrev_b32_e32 v63, 16, v63
	v_lshlrev_b32_e32 v62, 16, v62
	v_pk_fma_f32 v[4:5], v[4:5], v[18:19], v[62:63]
	v_lshlrev_b32_e32 v20, 16, v86
	v_and_b32_e32 v21, 0xffff0000, v86
	v_lshlrev_b32_e32 v22, 16, v102
	v_mul_f32_e32 v16, 0xbfb8aa3b, v22
	v_exp_f32_e32 v16, v16
	v_and_b32_e32 v23, 0xffff0000, v102
	v_pk_add_f32 v[20:21], v[2:3], v[20:21]
	v_lshlrev_b32_e32 v18, 16, v103
	v_add_f32_e32 v16, 1.0, v16
	v_rcp_f32_e32 v24, v16
	v_mul_f32_e32 v16, 0xbfb8aa3b, v23
	v_exp_f32_e32 v16, v16
	v_and_b32_e32 v19, 0xffff0000, v103
	v_add_f32_e32 v16, 1.0, v16
	v_rcp_f32_e32 v25, v16
	s_nop 0
	v_pk_mul_f32 v[22:23], v[24:25], v[22:23]
	s_nop 0
	v_pk_mul_f32 v[20:21], v[20:21], v[22:23]
	s_nop 0
	v_cvt_pk_bf16_f32 v16, v20, v21
	v_lshlrev_b32_e32 v20, 16, v87
	v_and_b32_e32 v21, 0xffff0000, v87
	v_mul_f32_e32 v17, 0xbfb8aa3b, v18
	v_exp_f32_e32 v17, v17
	v_pk_add_f32 v[20:21], v[4:5], v[20:21]
	v_add_f32_e32 v17, 1.0, v17
	v_rcp_f32_e32 v22, v17
	v_mul_f32_e32 v17, 0xbfb8aa3b, v19
	v_exp_f32_e32 v17, v17
	s_nop 0
	v_add_f32_e32 v17, 1.0, v17
	v_rcp_f32_e32 v23, v17
	s_nop 0
	v_pk_mul_f32 v[18:19], v[22:23], v[18:19]
	s_nop 0
	v_pk_mul_f32 v[18:19], v[20:21], v[18:19]
	s_nop 0
	v_cvt_pk_bf16_f32 v17, v18, v19
	global_store_dwordx2 v[38:39], v[16:17], off
	s_waitcnt vmcnt(13)
	v_and_b32_e32 v19, 0xffff0000, v65
	v_and_b32_e32 v18, 0xffff0000, v64
	v_pk_add_f32 v[18:19], v[18:19], 1.0 op_sel_hi:[1,0] neg_lo:[1,0] neg_hi:[1,0]
	v_lshlrev_b32_e32 v65, 16, v65
	v_lshlrev_b32_e32 v64, 16, v64
	v_pk_fma_f32 v[2:3], v[2:3], v[18:19], v[64:65]
	v_and_b32_e32 v19, 0xffff0000, v67
	v_and_b32_e32 v18, 0xffff0000, v66
	v_pk_add_f32 v[18:19], v[18:19], 1.0 op_sel_hi:[1,0] neg_lo:[1,0] neg_hi:[1,0]
	v_lshlrev_b32_e32 v67, 16, v67
	v_lshlrev_b32_e32 v66, 16, v66
	v_pk_fma_f32 v[4:5], v[4:5], v[18:19], v[66:67]
	v_lshlrev_b32_e32 v20, 16, v88
	v_and_b32_e32 v21, 0xffff0000, v88
	v_lshlrev_b32_e32 v22, 16, v104
	v_mul_f32_e32 v16, 0xbfb8aa3b, v22
	v_exp_f32_e32 v16, v16
	v_and_b32_e32 v23, 0xffff0000, v104
	v_pk_add_f32 v[20:21], v[2:3], v[20:21]
	v_lshlrev_b32_e32 v18, 16, v105
	v_add_f32_e32 v16, 1.0, v16
	v_rcp_f32_e32 v24, v16
	v_mul_f32_e32 v16, 0xbfb8aa3b, v23
	v_exp_f32_e32 v16, v16
	v_and_b32_e32 v19, 0xffff0000, v105
	v_add_f32_e32 v16, 1.0, v16
	v_rcp_f32_e32 v25, v16
	s_nop 0
	v_pk_mul_f32 v[22:23], v[24:25], v[22:23]
	s_nop 0
	v_pk_mul_f32 v[20:21], v[20:21], v[22:23]
	s_nop 0
	v_cvt_pk_bf16_f32 v16, v20, v21
	v_lshlrev_b32_e32 v20, 16, v89
	v_and_b32_e32 v21, 0xffff0000, v89
	v_mul_f32_e32 v17, 0xbfb8aa3b, v18
	v_exp_f32_e32 v17, v17
	v_pk_add_f32 v[20:21], v[4:5], v[20:21]
	v_add_f32_e32 v17, 1.0, v17
	v_rcp_f32_e32 v22, v17
	v_mul_f32_e32 v17, 0xbfb8aa3b, v19
	v_exp_f32_e32 v17, v17
	s_nop 0
	v_add_f32_e32 v17, 1.0, v17
	v_rcp_f32_e32 v23, v17
	s_nop 0
	v_pk_mul_f32 v[18:19], v[22:23], v[18:19]
	s_nop 0
	v_pk_mul_f32 v[18:19], v[20:21], v[18:19]
	s_nop 0
	v_cvt_pk_bf16_f32 v17, v18, v19
	global_store_dwordx2 v[40:41], v[16:17], off
	s_waitcnt vmcnt(11)
; __device__ __forceinline__ unsigned pk2(float a, float b) { return cvtpk(a, b); }
; __device__ __forceinline__ float blo(unsigned u) { return __uint_as_float(u << 16); }
; __device__ __forceinline__ float bhi(unsigned u) { return __uint_as_float(u & 0xffff0000u); }
; __device__ __forceinline__ float siluf(float x) { return x * sigm(x); }
; __device__ __forceinline__ void ph_lru_s3(const P& p, int d) {
;     ...
;     for (int q = 0; q < 64; q++) { size_t o = (size_t)rowmap(d, b, cc * 64 + q) * 1280 + ch; uint4 u = *(const uint4*)(AB + o);
;       h.x = (1.f - bhi(u.x)) * h.x + blo(u.x); h.y = (1.f - bhi(u.y)) * h.y + blo(u.y); h.z = (1.f - bhi(u.z)) * h.z + blo(u.z); h.w = (1.f - bhi(u.w)) * h.w + blo(u.w);
;       if (d == 0) *(uint2*)(HF + o) = uint2{pk2(h.x, h.y), pk2(h.z, h.w)};
;       else { uint2 hf = *(const uint2*)(HF + o), zz = *(const uint2*)(Z + o);
;         *(uint2*)(Z + o) = uint2{pk2((blo(hf.x) + h.x) * siluf(blo(zz.x)), (bhi(hf.x) + h.y) * siluf(bhi(zz.x))), pk2((blo(hf.y) + h.z) * siluf(blo(zz.y)), (bhi(hf.y) + h.w) * siluf(bhi(zz.y)))}; } }
	v_and_b32_e32 v19, 0xffff0000, v69
	v_and_b32_e32 v18, 0xffff0000, v68
	v_pk_add_f32 v[18:19], v[18:19], 1.0 op_sel_hi:[1,0] neg_lo:[1,0] neg_hi:[1,0]
	v_lshlrev_b32_e32 v69, 16, v69
	v_lshlrev_b32_e32 v68, 16, v68
	v_pk_fma_f32 v[2:3], v[2:3], v[18:19], v[68:69]
	v_and_b32_e32 v19, 0xffff0000, v71
	v_and_b32_e32 v18, 0xffff0000, v70
	v_pk_add_f32 v[18:19], v[18:19], 1.0 op_sel_hi:[1,0] neg_lo:[1,0] neg_hi:[1,0]
	v_lshlrev_b32_e32 v71, 16, v71
	v_lshlrev_b32_e32 v70, 16, v70
	v_pk_fma_f32 v[4:5], v[4:5], v[18:19], v[70:71]
	v_lshlrev_b32_e32 v20, 16, v90
	v_and_b32_e32 v21, 0xffff0000, v90
	v_lshlrev_b32_e32 v22, 16, v106
	v_mul_f32_e32 v16, 0xbfb8aa3b, v22
	v_exp_f32_e32 v16, v16
	v_and_b32_e32 v23, 0xffff0000, v106
	v_pk_add_f32 v[20:21], v[2:3], v[20:21]
	v_lshlrev_b32_e32 v18, 16, v107
	v_add_f32_e32 v16, 1.0, v16
	v_rcp_f32_e32 v24, v16
	v_mul_f32_e32 v16, 0xbfb8aa3b, v23
	v_exp_f32_e32 v16, v16
	v_and_b32_e32 v19, 0xffff0000, v107
	v_add_f32_e32 v16, 1.0, v16
	v_rcp_f32_e32 v25, v16
	s_nop 0
	v_pk_mul_f32 v[22:23], v[24:25], v[22:23]
	s_nop 0
	v_pk_mul_f32 v[20:21], v[20:21], v[22:23]
	s_nop 0
	v_cvt_pk_bf16_f32 v16, v20, v21
	v_lshlrev_b32_e32 v20, 16, v91
	v_and_b32_e32 v21, 0xffff0000, v91
	v_mul_f32_e32 v17, 0xbfb8aa3b, v18
	v_exp_f32_e32 v17, v17
	v_pk_add_f32 v[20:21], v[4:5], v[20:21]
	v_add_f32_e32 v17, 1.0, v17
	v_rcp_f32_e32 v22, v17
	v_mul_f32_e32 v17, 0xbfb8aa3b, v19
	v_exp_f32_e32 v17, v17
	s_nop 0
	v_add_f32_e32 v17, 1.0, v17
	v_rcp_f32_e32 v23, v17
	s_nop 0
	v_pk_mul_f32 v[18:19], v[22:23], v[18:19]
	s_nop 0
	v_pk_mul_f32 v[18:19], v[20:21], v[18:19]
	s_nop 0
	v_cvt_pk_bf16_f32 v17, v18, v19
	global_store_dwordx2 v[42:43], v[16:17], off
	s_waitcnt vmcnt(9)
	v_and_b32_e32 v19, 0xffff0000, v73
	v_and_b32_e32 v18, 0xffff0000, v72
	v_pk_add_f32 v[18:19], v[18:19], 1.0 op_sel_hi:[1,0] neg_lo:[1,0] neg_hi:[1,0]
	v_lshlrev_b32_e32 v73, 16, v73
	v_lshlrev_b32_e32 v72, 16, v72
	v_pk_fma_f32 v[2:3], v[2:3], v[18:19], v[72:73]
	v_and_b32_e32 v19, 0xffff0000, v75
	v_and_b32_e32 v18, 0xffff0000, v74
	v_pk_add_f32 v[18:19], v[18:19], 1.0 op_sel_hi:[1,0] neg_lo:[1,0] neg_hi:[1,0]
	v_lshlrev_b32_e32 v75, 16, v75
	v_lshlrev_b32_e32 v74, 16, v74
	v_pk_fma_f32 v[4:5], v[4:5], v[18:19], v[74:75]
	v_lshlrev_b32_e32 v20, 16, v92
	v_and_b32_e32 v21, 0xffff0000, v92
	v_lshlrev_b32_e32 v22, 16, v108
	v_mul_f32_e32 v16, 0xbfb8aa3b, v22
	v_exp_f32_e32 v16, v16
	v_and_b32_e32 v23, 0xffff0000, v108
	v_pk_add_f32 v[20:21], v[2:3], v[20:21]
	v_lshlrev_b32_e32 v18, 16, v109
	v_add_f32_e32 v16, 1.0, v16
	v_rcp_f32_e32 v24, v16
	v_mul_f32_e32 v16, 0xbfb8aa3b, v23
	v_exp_f32_e32 v16, v16
	v_and_b32_e32 v19, 0xffff0000, v109
	v_add_f32_e32 v16, 1.0, v16
	v_rcp_f32_e32 v25, v16
	s_nop 0
	v_pk_mul_f32 v[22:23], v[24:25], v[22:23]
	s_nop 0
	v_pk_mul_f32 v[20:21], v[20:21], v[22:23]
	s_nop 0
	v_cvt_pk_bf16_f32 v16, v20, v21
	v_lshlrev_b32_e32 v20, 16, v93
	v_and_b32_e32 v21, 0xffff0000, v93
	v_mul_f32_e32 v17, 0xbfb8aa3b, v18
	v_exp_f32_e32 v17, v17
	v_pk_add_f32 v[20:21], v[4:5], v[20:21]
	v_add_f32_e32 v17, 1.0, v17
	v_rcp_f32_e32 v22, v17
	v_mul_f32_e32 v17, 0xbfb8aa3b, v19
	v_exp_f32_e32 v17, v17
	s_nop 0
	v_add_f32_e32 v17, 1.0, v17
	v_rcp_f32_e32 v23, v17
	s_nop 0
	v_pk_mul_f32 v[18:19], v[22:23], v[18:19]
	s_nop 0
	v_pk_mul_f32 v[18:19], v[20:21], v[18:19]
	s_nop 0
	v_cvt_pk_bf16_f32 v17, v18, v19
	global_store_dwordx2 v[44:45], v[16:17], off
	s_waitcnt vmcnt(7)
	v_and_b32_e32 v19, 0xffff0000, v77
	v_and_b32_e32 v18, 0xffff0000, v76
	v_pk_add_f32 v[18:19], v[18:19], 1.0 op_sel_hi:[1,0] neg_lo:[1,0] neg_hi:[1,0]
	v_lshlrev_b32_e32 v77, 16, v77
	v_lshlrev_b32_e32 v76, 16, v76
	v_pk_fma_f32 v[2:3], v[2:3], v[18:19], v[76:77]
	v_and_b32_e32 v19, 0xffff0000, v79
	v_and_b32_e32 v18, 0xffff0000, v78
	v_pk_add_f32 v[18:19], v[18:19], 1.0 op_sel_hi:[1,0] neg_lo:[1,0] neg_hi:[1,0]
	v_lshlrev_b32_e32 v79, 16, v79
	v_lshlrev_b32_e32 v78, 16, v78
	v_pk_fma_f32 v[4:5], v[4:5], v[18:19], v[78:79]
	v_lshlrev_b32_e32 v20, 16, v94
	v_and_b32_e32 v21, 0xffff0000, v94
	v_lshlrev_b32_e32 v22, 16, v110
	v_mul_f32_e32 v16, 0xbfb8aa3b, v22
	v_exp_f32_e32 v16, v16
	v_and_b32_e32 v23, 0xffff0000, v110
	v_pk_add_f32 v[20:21], v[2:3], v[20:21]
	v_lshlrev_b32_e32 v18, 16, v111
	v_add_f32_e32 v16, 1.0, v16
	v_rcp_f32_e32 v24, v16
	v_mul_f32_e32 v16, 0xbfb8aa3b, v23
	v_exp_f32_e32 v16, v16
	v_and_b32_e32 v19, 0xffff0000, v111
	v_add_f32_e32 v16, 1.0, v16
	v_rcp_f32_e32 v25, v16
	s_nop 0
	v_pk_mul_f32 v[22:23], v[24:25], v[22:23]
	s_nop 0
	v_pk_mul_f32 v[20:21], v[20:21], v[22:23]
	s_nop 0
	v_cvt_pk_bf16_f32 v16, v20, v21
	v_lshlrev_b32_e32 v20, 16, v95
	v_and_b32_e32 v21, 0xffff0000, v95
	v_mul_f32_e32 v17, 0xbfb8aa3b, v18
	v_exp_f32_e32 v17, v17
	v_pk_add_f32 v[20:21], v[4:5], v[20:21]
	v_add_f32_e32 v17, 1.0, v17
	v_rcp_f32_e32 v22, v17
	v_mul_f32_e32 v17, 0xbfb8aa3b, v19
	v_exp_f32_e32 v17, v17
	s_nop 0
	v_add_f32_e32 v17, 1.0, v17
	v_rcp_f32_e32 v23, v17
	s_nop 0
	v_pk_mul_f32 v[18:19], v[22:23], v[18:19]
	s_nop 0
	v_pk_mul_f32 v[18:19], v[20:21], v[18:19]
	s_nop 0
	v_cvt_pk_bf16_f32 v17, v18, v19
	global_store_dwordx2 v[46:47], v[16:17], off
	s_branch .LBB0_1484

; __device__ __forceinline__ void ph_lru_s2(const P& p, char* smem) {
;     ...
;     const int b = it / 20, ch = (it % 20) * 64 + chl; const int cb = seg * 33, ce = cb + 33 < NCH_ ? cb + 33 : NCH_;
;     float Pp = 1.f, Q = 0.f;
; #pragma unroll 11
;     for (int cc = cb; cc < ce; cc++) { float2 a = AGG[(size_t)(b * NCH_ + cc) * 1280 + ch]; Pp *= a.x; Q = a.x * Q + a.y; }
.LBB0_1529:
	s_or_b64 exec, exec, s[8:9]
	s_and_saveexec_b64 s[8:9], s[44:45]
	s_cbranch_execz .LBB0_1533
	v_lshl_or_b32 v6, s12, 6, v0
	s_mul_i32 s10, s19, 0x500
	v_subrev_u32_e32 v6, s10, v6
	v_ashrrev_i32_e32 v3, 31, v2
	v_ashrrev_i32_e32 v7, 31, v6
	v_lshl_add_u64 v[4:5], v[2:3], 3, s[0:1]
	v_add_u32_e32 v3, s13, v17
	v_lshlrev_b64 v[6:7], 3, v[6:7]
	v_mad_i64_i32 v[6:7], s[10:11], v3, s16, v[6:7]
	v_lshl_add_u64 v[6:7], s[0:1], 0, v[6:7]
	s_mov_b64 s[10:11], 0
	s_mov_b64 s[48:49], 0x1b800
	s_mov_b64 s[30:31], 0x2800
.LBB0_1531:
	global_load_dwordx2 v[24:25], v[6:7], off
	v_lshl_add_u64 v[22:23], v[6:7], 0, s[30:31]
	global_load_dwordx2 v[26:27], v[22:23], off
	v_lshl_add_u64 v[22:23], v[22:23], 0, s[30:31]
	global_load_dwordx2 v[28:29], v[22:23], off
	v_lshl_add_u64 v[22:23], v[22:23], 0, s[30:31]
	global_load_dwordx2 v[30:31], v[22:23], off
	v_lshl_add_u64 v[22:23], v[22:23], 0, s[30:31]
	global_load_dwordx2 v[32:33], v[22:23], off
	v_lshl_add_u64 v[22:23], v[22:23], 0, s[30:31]
	global_load_dwordx2 v[34:35], v[22:23], off
	v_lshl_add_u64 v[22:23], v[22:23], 0, s[30:31]
	global_load_dwordx2 v[36:37], v[22:23], off
	v_lshl_add_u64 v[22:23], v[22:23], 0, s[30:31]
	global_load_dwordx2 v[38:39], v[22:23], off
	v_lshl_add_u64 v[22:23], v[22:23], 0, s[30:31]
	global_load_dwordx2 v[40:41], v[22:23], off
	v_lshl_add_u64 v[22:23], v[22:23], 0, s[30:31]
	global_load_dwordx2 v[42:43], v[22:23], off
	v_lshl_add_u64 v[22:23], v[22:23], 0, s[30:31]
	global_load_dwordx2 v[44:45], v[22:23], off
	v_add_u32_e32 v17, 11, v17
	v_cmp_ge_i32_e64 s[46:47], v17, v12
	v_lshl_add_u64 v[6:7], v[6:7], 0, s[48:49]
	s_or_b64 s[10:11], s[46:47], s[10:11]
	s_waitcnt vmcnt(10)
	v_fmac_f32_e32 v25, v9, v24
	v_mul_f32_e32 v18, v18, v24
	s_waitcnt vmcnt(9)
	v_fmac_f32_e32 v27, v25, v26
	v_mul_f32_e32 v18, v18, v26
	s_waitcnt vmcnt(8)
	v_fmac_f32_e32 v29, v27, v28
	v_mul_f32_e32 v18, v18, v28
	s_waitcnt vmcnt(7)
	v_fmac_f32_e32 v31, v29, v30
	v_mul_f32_e32 v18, v18, v30
	s_waitcnt vmcnt(6)
	v_fmac_f32_e32 v33, v31, v32
	v_mul_f32_e32 v18, v18, v32
	s_waitcnt vmcnt(5)
	v_fmac_f32_e32 v35, v33, v34
	v_mul_f32_e32 v18, v18, v34
	s_waitcnt vmcnt(4)
	v_fmac_f32_e32 v37, v35, v36
	v_mul_f32_e32 v18, v18, v36
	s_waitcnt vmcnt(3)
	v_fmac_f32_e32 v39, v37, v38
	v_mul_f32_e32 v18, v18, v38
	s_waitcnt vmcnt(2)
	v_fmac_f32_e32 v41, v39, v40
	v_mul_f32_e32 v18, v18, v40
	s_waitcnt vmcnt(1)
	v_fmac_f32_e32 v43, v41, v42
	v_mul_f32_e32 v18, v18, v42
	s_waitcnt vmcnt(0)
	v_fmac_f32_e32 v45, v43, v44
	v_mul_f32_e32 v18, v18, v44
	v_mov_b32_e32 v9, v45
	s_andn2_b64 exec, exec, s[10:11]
	s_cbranch_execnz .LBB0_1531
	s_or_b64 exec, exec, s[10:11]

; __device__ __forceinline__ void ph_lru_s2(const P& p, char* smem) {
;     ...
;     float h = 0.f;
;     for (int s2 = 0; s2 < seg; s2++) h = sP[s2 * 64 + chl] * h + sQ[s2 * 64 + chl];
; #pragma unroll 11
;     for (int cc = cb; cc < ce; cc++) { size_t o = (size_t)(b * NCH_ + cc) * 1280 + ch; float2 a = AGG[o]; CAR[o] = h; h = a.x * h + a.y; }
.LBB0_1543:
	s_or_b64 exec, exec, s[8:9]
	s_and_b64 s[8:9], exec, s[44:45]
	s_mov_b64 s[30:31], 0x1b800
	s_mov_b64 exec, s[8:9]
	s_cbranch_execz .LBB0_1523
	v_subrev_u32_e32 v6, s19, v8
	v_ashrrev_i32_e32 v7, 31, v6
	v_add_u32_e32 v18, s13, v17
	v_lshlrev_b64 v[4:5], 3, v[6:7]
	v_lshlrev_b64 v[6:7], 2, v[6:7]
	v_mad_i64_i32 v[4:5], s[8:9], v18, s16, v[4:5]
	v_mad_i64_i32 v[6:7], s[8:9], v18, s95, v[6:7]
	v_ashrrev_i32_e32 v3, 31, v2
	v_lshl_add_u64 v[4:5], s[0:1], 0, v[4:5]
	v_lshl_add_u64 v[6:7], s[34:35], 0, v[6:7]
	s_mov_b64 s[8:9], 0
	s_mov_b64 s[48:49], 0x2800
	s_mov_b64 s[10:11], 0x1400
.LBB0_1545:
	global_load_dwordx2 v[24:25], v[4:5], off
	v_lshl_add_u64 v[22:23], v[4:5], 0, s[48:49]
	global_load_dwordx2 v[26:27], v[22:23], off
	v_lshl_add_u64 v[22:23], v[22:23], 0, s[48:49]
	global_load_dwordx2 v[28:29], v[22:23], off
	v_lshl_add_u64 v[22:23], v[22:23], 0, s[48:49]
	global_load_dwordx2 v[30:31], v[22:23], off
	v_lshl_add_u64 v[22:23], v[22:23], 0, s[48:49]
	global_load_dwordx2 v[32:33], v[22:23], off
	v_lshl_add_u64 v[22:23], v[22:23], 0, s[48:49]
	global_load_dwordx2 v[34:35], v[22:23], off
	v_lshl_add_u64 v[22:23], v[22:23], 0, s[48:49]
	global_load_dwordx2 v[36:37], v[22:23], off
	v_lshl_add_u64 v[22:23], v[22:23], 0, s[48:49]
	global_load_dwordx2 v[38:39], v[22:23], off
	v_lshl_add_u64 v[22:23], v[22:23], 0, s[48:49]
	global_load_dwordx2 v[40:41], v[22:23], off
	v_lshl_add_u64 v[22:23], v[22:23], 0, s[48:49]
	global_load_dwordx2 v[42:43], v[22:23], off
	v_lshl_add_u64 v[22:23], v[22:23], 0, s[48:49]
	global_load_dwordx2 v[44:45], v[22:23], off
	v_add_u32_e32 v17, 11, v17
	v_cmp_ge_i32_e64 s[46:47], v17, v12
	v_lshl_add_u64 v[4:5], v[4:5], 0, s[30:31]
	s_or_b64 s[8:9], s[46:47], s[8:9]
	v_mov_b64_e32 v[46:47], v[6:7]
	global_store_dword v[46:47], v9, off
	v_lshl_add_u64 v[48:49], v[46:47], 0, s[10:11]
	s_waitcnt vmcnt(11)
	v_fmac_f32_e32 v25, v9, v24
	global_store_dword v[48:49], v25, off
	v_lshl_add_u64 v[46:47], v[48:49], 0, s[10:11]
	s_waitcnt vmcnt(11)
	v_fmac_f32_e32 v27, v25, v26
	global_store_dword v[46:47], v27, off
	v_lshl_add_u64 v[48:49], v[46:47], 0, s[10:11]
	s_waitcnt vmcnt(11)
	v_fmac_f32_e32 v29, v27, v28
	global_store_dword v[48:49], v29, off
	v_lshl_add_u64 v[46:47], v[48:49], 0, s[10:11]
	s_waitcnt vmcnt(11)
	v_fmac_f32_e32 v31, v29, v30
	global_store_dword v[46:47], v31, off
	v_lshl_add_u64 v[48:49], v[46:47], 0, s[10:11]
	s_waitcnt vmcnt(11)
	v_fmac_f32_e32 v33, v31, v32
	global_store_dword v[48:49], v33, off
	v_lshl_add_u64 v[46:47], v[48:49], 0, s[10:11]
	s_waitcnt vmcnt(11)
	v_fmac_f32_e32 v35, v33, v34
	global_store_dword v[46:47], v35, off
	v_lshl_add_u64 v[48:49], v[46:47], 0, s[10:11]
	s_waitcnt vmcnt(11)
	v_fmac_f32_e32 v37, v35, v36
	global_store_dword v[48:49], v37, off
	v_lshl_add_u64 v[46:47], v[48:49], 0, s[10:11]
	s_waitcnt vmcnt(11)
	v_fmac_f32_e32 v39, v37, v38
	global_store_dword v[46:47], v39, off
	v_lshl_add_u64 v[48:49], v[46:47], 0, s[10:11]
	s_waitcnt vmcnt(11)
	v_fmac_f32_e32 v41, v39, v40
	global_store_dword v[48:49], v41, off
	v_lshl_add_u64 v[46:47], v[48:49], 0, s[10:11]
	s_waitcnt vmcnt(11)
	v_fmac_f32_e32 v43, v41, v42
	global_store_dword v[46:47], v43, off
	v_lshl_add_u64 v[48:49], v[46:47], 0, s[10:11]
	s_waitcnt vmcnt(11)
	v_fmac_f32_e32 v45, v43, v44
	v_mov_b32_e32 v9, v45
	v_mov_b64_e32 v[6:7], v[48:49]
	s_andn2_b64 exec, exec, s[8:9]
	s_cbranch_execnz .LBB0_1545
	s_branch .LBB0_1523

; __device__ __forceinline__ float blo(unsigned u) { return __uint_as_float(u << 16); }
; __device__ __forceinline__ float bhi(unsigned u) { return __uint_as_float(u & 0xffff0000u); }
; __device__ __forceinline__ void ph_lru_s1(const P& p, int d) {
;     ...
; #pragma unroll 8
;     for (int q = 0; q < 64; q++) { uint4 u = *(const uint4*)(AB + (size_t)rowmap(d, b, cc * 64 + q) * 1280 + ch);
;       float a0 = 1.f - bhi(u.x), a1 = 1.f - bhi(u.y), a2 = 1.f - bhi(u.z), a3 = 1.f - bhi(u.w);
;       P0 *= a0; Q0 = a0 * Q0 + blo(u.x); P1 *= a1; Q1 = a1 * Q1 + blo(u.y); P2 *= a2; Q2 = a2 * Q2 + blo(u.z); P3 *= a3; Q3 = a3 * Q3 + blo(u.w); }
.LBB0_1551:
	v_add_u32_e32 v3, -7, v23
	v_cmp_lt_i32_e64 s[40:41], s15, v3
	v_sub_u32_e32 v14, v176, v3
	v_sub_u32_e32 v7, v177, v3
	v_cndmask_b32_e64 v7, v14, v7, s[40:41]
	v_cndmask_b32_e32 v3, v7, v3, vcc
	v_add_u32_e32 v3, v3, v22
	v_mad_i64_i32 v[72:73], s[12:13], v3, s95, v[12:13]
	global_load_dwordx4 v[40:43], v[72:73], off
	v_add_u32_e32 v3, -6, v23
	v_cmp_lt_i32_e64 s[40:41], s15, v3
	v_sub_u32_e32 v14, v176, v3
	v_sub_u32_e32 v7, v177, v3
	v_cndmask_b32_e64 v7, v14, v7, s[40:41]
	v_cndmask_b32_e32 v3, v7, v3, vcc
	v_add_u32_e32 v3, v3, v22
	v_mad_i64_i32 v[72:73], s[12:13], v3, s95, v[12:13]
	global_load_dwordx4 v[44:47], v[72:73], off
	v_add_u32_e32 v3, -5, v23
	v_cmp_lt_i32_e64 s[40:41], s15, v3
	v_sub_u32_e32 v14, v176, v3
	v_sub_u32_e32 v7, v177, v3
	v_cndmask_b32_e64 v7, v14, v7, s[40:41]
	v_cndmask_b32_e32 v3, v7, v3, vcc
	v_add_u32_e32 v3, v3, v22
	v_mad_i64_i32 v[72:73], s[12:13], v3, s95, v[12:13]
	global_load_dwordx4 v[48:51], v[72:73], off
	v_add_u32_e32 v3, -4, v23
	v_cmp_lt_i32_e64 s[40:41], s15, v3
	v_sub_u32_e32 v14, v176, v3
	v_sub_u32_e32 v7, v177, v3
	v_cndmask_b32_e64 v7, v14, v7, s[40:41]
	v_cndmask_b32_e32 v3, v7, v3, vcc
	v_add_u32_e32 v3, v3, v22
	v_mad_i64_i32 v[72:73], s[12:13], v3, s95, v[12:13]
	global_load_dwordx4 v[52:55], v[72:73], off
	v_add_u32_e32 v3, -3, v23
	v_cmp_lt_i32_e64 s[40:41], s15, v3
	v_sub_u32_e32 v14, v176, v3
	v_sub_u32_e32 v7, v177, v3
	v_cndmask_b32_e64 v7, v14, v7, s[40:41]
	v_cndmask_b32_e32 v3, v7, v3, vcc
	v_add_u32_e32 v3, v3, v22
	v_mad_i64_i32 v[72:73], s[12:13], v3, s95, v[12:13]
	global_load_dwordx4 v[56:59], v[72:73], off
	v_add_u32_e32 v3, -2, v23
	v_cmp_lt_i32_e64 s[40:41], s15, v3
	v_sub_u32_e32 v14, v176, v3
	v_sub_u32_e32 v7, v177, v3
	v_cndmask_b32_e64 v7, v14, v7, s[40:41]
	v_cndmask_b32_e32 v3, v7, v3, vcc
	v_add_u32_e32 v3, v3, v22
	v_mad_i64_i32 v[72:73], s[12:13], v3, s95, v[12:13]
	global_load_dwordx4 v[60:63], v[72:73], off
	v_add_u32_e32 v3, -1, v23
	v_cmp_lt_i32_e64 s[40:41], s15, v3
	v_sub_u32_e32 v14, v176, v3
	v_sub_u32_e32 v7, v177, v3
	v_cndmask_b32_e64 v7, v14, v7, s[40:41]
	v_cndmask_b32_e32 v3, v7, v3, vcc
	v_add_u32_e32 v3, v3, v22
	v_mad_i64_i32 v[72:73], s[12:13], v3, s95, v[12:13]
	global_load_dwordx4 v[64:67], v[72:73], off
	v_mov_b32_e32 v3, v23
	v_cmp_lt_i32_e64 s[40:41], s15, v3
	v_sub_u32_e32 v14, v176, v3
	v_sub_u32_e32 v7, v177, v3
	v_cndmask_b32_e64 v7, v14, v7, s[40:41]
	v_cndmask_b32_e32 v3, v7, v3, vcc
	v_add_u32_e32 v3, v3, v22
	v_mad_i64_i32 v[72:73], s[12:13], v3, s95, v[12:13]
	global_load_dwordx4 v[68:71], v[72:73], off
	s_waitcnt vmcnt(7)
	v_and_b32_e32 v26, 0xffff0000, v40
	v_and_b32_e32 v27, 0xffff0000, v41
	v_and_b32_e32 v28, 0xffff0000, v42
	v_and_b32_e32 v29, 0xffff0000, v43
	v_sub_f32_e32 v26, 1.0, v26
	v_sub_f32_e32 v27, 1.0, v27
	v_sub_f32_e32 v28, 1.0, v28
	v_sub_f32_e32 v29, 1.0, v29
	v_lshlrev_b32_e32 v40, 16, v40
	v_lshlrev_b32_e32 v41, 16, v41
	v_lshlrev_b32_e32 v42, 16, v42
	v_lshlrev_b32_e32 v43, 16, v43
	v_mul_f32_e32 v6, v6, v26
	v_mul_f32_e32 v8, v8, v27
	v_mul_f32_e32 v2, v2, v28
	v_mul_f32_e32 v4, v4, v29
	v_mul_f32_e32 v5, v5, v26
	v_mul_f32_e32 v19, v19, v27
	v_mul_f32_e32 v15, v15, v28
	v_mul_f32_e32 v17, v17, v29
	v_add_f32_e32 v5, v40, v5
	v_add_f32_e32 v19, v41, v19
	v_add_f32_e32 v15, v42, v15
	v_add_f32_e32 v17, v43, v17
	s_waitcnt vmcnt(6)
	v_and_b32_e32 v26, 0xffff0000, v44
	v_and_b32_e32 v27, 0xffff0000, v45
	v_and_b32_e32 v28, 0xffff0000, v46
	v_and_b32_e32 v29, 0xffff0000, v47
	v_sub_f32_e32 v26, 1.0, v26
	v_sub_f32_e32 v27, 1.0, v27
	v_sub_f32_e32 v28, 1.0, v28
	v_sub_f32_e32 v29, 1.0, v29
	v_lshlrev_b32_e32 v44, 16, v44
	v_lshlrev_b32_e32 v45, 16, v45
	v_lshlrev_b32_e32 v46, 16, v46
	v_lshlrev_b32_e32 v47, 16, v47
	v_mul_f32_e32 v6, v6, v26
	v_mul_f32_e32 v8, v8, v27
	v_mul_f32_e32 v2, v2, v28
	v_mul_f32_e32 v4, v4, v29
	v_mul_f32_e32 v5, v5, v26
	v_mul_f32_e32 v19, v19, v27
	v_mul_f32_e32 v15, v15, v28
	v_mul_f32_e32 v17, v17, v29
	v_add_f32_e32 v5, v44, v5
	v_add_f32_e32 v19, v45, v19
	v_add_f32_e32 v15, v46, v15
	v_add_f32_e32 v17, v47, v17
	s_waitcnt vmcnt(5)
	v_and_b32_e32 v26, 0xffff0000, v48
	v_and_b32_e32 v27, 0xffff0000, v49
	v_and_b32_e32 v28, 0xffff0000, v50
	v_and_b32_e32 v29, 0xffff0000, v51
	v_sub_f32_e32 v26, 1.0, v26
	v_sub_f32_e32 v27, 1.0, v27
	v_sub_f32_e32 v28, 1.0, v28
	v_sub_f32_e32 v29, 1.0, v29
	v_lshlrev_b32_e32 v48, 16, v48
	v_lshlrev_b32_e32 v49, 16, v49
	v_lshlrev_b32_e32 v50, 16, v50
	v_lshlrev_b32_e32 v51, 16, v51
	v_mul_f32_e32 v6, v6, v26
	v_mul_f32_e32 v8, v8, v27
	v_mul_f32_e32 v2, v2, v28
	v_mul_f32_e32 v4, v4, v29
	v_mul_f32_e32 v5, v5, v26
	v_mul_f32_e32 v19, v19, v27
	v_mul_f32_e32 v15, v15, v28
	v_mul_f32_e32 v17, v17, v29
	v_add_f32_e32 v5, v48, v5
	v_add_f32_e32 v19, v49, v19
	v_add_f32_e32 v15, v50, v15
	v_add_f32_e32 v17, v51, v17
	s_waitcnt vmcnt(4)
; __device__ __forceinline__ float blo(unsigned u) { return __uint_as_float(u << 16); }
; __device__ __forceinline__ float bhi(unsigned u) { return __uint_as_float(u & 0xffff0000u); }
; __device__ __forceinline__ void ph_lru_s1(const P& p, int d) {
;     ...
; #pragma unroll 8
;     for (int q = 0; q < 64; q++) { uint4 u = *(const uint4*)(AB + (size_t)rowmap(d, b, cc * 64 + q) * 1280 + ch);
;       float a0 = 1.f - bhi(u.x), a1 = 1.f - bhi(u.y), a2 = 1.f - bhi(u.z), a3 = 1.f - bhi(u.w);
;       P0 *= a0; Q0 = a0 * Q0 + blo(u.x); P1 *= a1; Q1 = a1 * Q1 + blo(u.y); P2 *= a2; Q2 = a2 * Q2 + blo(u.z); P3 *= a3; Q3 = a3 * Q3 + blo(u.w); }
;     float4* ag = (float4*)(AGG + (size_t)(b * NCH_ + cc) * 1280 + ch); ag[0] = float4{P0, Q0, P1, Q1}; ag[1] = float4{P2, Q2, P3, Q3};
	v_and_b32_e32 v26, 0xffff0000, v52
	v_and_b32_e32 v27, 0xffff0000, v53
	v_and_b32_e32 v28, 0xffff0000, v54
	v_and_b32_e32 v29, 0xffff0000, v55
	v_sub_f32_e32 v26, 1.0, v26
	v_sub_f32_e32 v27, 1.0, v27
	v_sub_f32_e32 v28, 1.0, v28
	v_sub_f32_e32 v29, 1.0, v29
	v_lshlrev_b32_e32 v52, 16, v52
	v_lshlrev_b32_e32 v53, 16, v53
	v_lshlrev_b32_e32 v54, 16, v54
	v_lshlrev_b32_e32 v55, 16, v55
	v_mul_f32_e32 v6, v6, v26
	v_mul_f32_e32 v8, v8, v27
	v_mul_f32_e32 v2, v2, v28
	v_mul_f32_e32 v4, v4, v29
	v_mul_f32_e32 v5, v5, v26
	v_mul_f32_e32 v19, v19, v27
	v_mul_f32_e32 v15, v15, v28
	v_mul_f32_e32 v17, v17, v29
	v_add_f32_e32 v5, v52, v5
	v_add_f32_e32 v19, v53, v19
	v_add_f32_e32 v15, v54, v15
	v_add_f32_e32 v17, v55, v17
	s_waitcnt vmcnt(3)
	v_and_b32_e32 v26, 0xffff0000, v56
	v_and_b32_e32 v27, 0xffff0000, v57
	v_and_b32_e32 v28, 0xffff0000, v58
	v_and_b32_e32 v29, 0xffff0000, v59
	v_sub_f32_e32 v26, 1.0, v26
	v_sub_f32_e32 v27, 1.0, v27
	v_sub_f32_e32 v28, 1.0, v28
	v_sub_f32_e32 v29, 1.0, v29
	v_lshlrev_b32_e32 v56, 16, v56
	v_lshlrev_b32_e32 v57, 16, v57
	v_lshlrev_b32_e32 v58, 16, v58
	v_lshlrev_b32_e32 v59, 16, v59
	v_mul_f32_e32 v6, v6, v26
	v_mul_f32_e32 v8, v8, v27
	v_mul_f32_e32 v2, v2, v28
	v_mul_f32_e32 v4, v4, v29
	v_mul_f32_e32 v5, v5, v26
	v_mul_f32_e32 v19, v19, v27
	v_mul_f32_e32 v15, v15, v28
	v_mul_f32_e32 v17, v17, v29
	v_add_f32_e32 v5, v56, v5
	v_add_f32_e32 v19, v57, v19
	v_add_f32_e32 v15, v58, v15
	v_add_f32_e32 v17, v59, v17
	s_waitcnt vmcnt(2)
	v_and_b32_e32 v26, 0xffff0000, v60
	v_and_b32_e32 v27, 0xffff0000, v61
	v_and_b32_e32 v28, 0xffff0000, v62
	v_and_b32_e32 v29, 0xffff0000, v63
	v_sub_f32_e32 v26, 1.0, v26
	v_sub_f32_e32 v27, 1.0, v27
	v_sub_f32_e32 v28, 1.0, v28
	v_sub_f32_e32 v29, 1.0, v29
	v_lshlrev_b32_e32 v60, 16, v60
	v_lshlrev_b32_e32 v61, 16, v61
	v_lshlrev_b32_e32 v62, 16, v62
	v_lshlrev_b32_e32 v63, 16, v63
	v_mul_f32_e32 v6, v6, v26
	v_mul_f32_e32 v8, v8, v27
	v_mul_f32_e32 v2, v2, v28
	v_mul_f32_e32 v4, v4, v29
	v_mul_f32_e32 v5, v5, v26
	v_mul_f32_e32 v19, v19, v27
	v_mul_f32_e32 v15, v15, v28
	v_mul_f32_e32 v17, v17, v29
	v_add_f32_e32 v5, v60, v5
	v_add_f32_e32 v19, v61, v19
	v_add_f32_e32 v15, v62, v15
	v_add_f32_e32 v17, v63, v17
	s_waitcnt vmcnt(1)
	v_and_b32_e32 v26, 0xffff0000, v64
	v_and_b32_e32 v27, 0xffff0000, v65
	v_and_b32_e32 v28, 0xffff0000, v66
	v_and_b32_e32 v29, 0xffff0000, v67
	v_sub_f32_e32 v26, 1.0, v26
	v_sub_f32_e32 v27, 1.0, v27
	v_sub_f32_e32 v28, 1.0, v28
	v_sub_f32_e32 v29, 1.0, v29
	v_lshlrev_b32_e32 v64, 16, v64
	v_lshlrev_b32_e32 v65, 16, v65
	v_lshlrev_b32_e32 v66, 16, v66
	v_lshlrev_b32_e32 v67, 16, v67
	v_mul_f32_e32 v6, v6, v26
	v_mul_f32_e32 v8, v8, v27
	v_mul_f32_e32 v2, v2, v28
	v_mul_f32_e32 v4, v4, v29
	v_mul_f32_e32 v5, v5, v26
	v_mul_f32_e32 v19, v19, v27
	v_mul_f32_e32 v15, v15, v28
	v_mul_f32_e32 v17, v17, v29
	v_add_f32_e32 v5, v64, v5
	v_add_f32_e32 v19, v65, v19
	v_add_f32_e32 v15, v66, v15
	v_add_f32_e32 v17, v67, v17
	s_waitcnt vmcnt(0)
	v_and_b32_e32 v26, 0xffff0000, v68
	v_and_b32_e32 v27, 0xffff0000, v69
	v_and_b32_e32 v28, 0xffff0000, v70
	v_and_b32_e32 v29, 0xffff0000, v71
	v_sub_f32_e32 v26, 1.0, v26
	v_sub_f32_e32 v27, 1.0, v27
	v_sub_f32_e32 v28, 1.0, v28
	v_sub_f32_e32 v29, 1.0, v29
	v_lshlrev_b32_e32 v68, 16, v68
	v_lshlrev_b32_e32 v69, 16, v69
	v_lshlrev_b32_e32 v70, 16, v70
	v_lshlrev_b32_e32 v71, 16, v71
	v_mul_f32_e32 v6, v6, v26
	v_mul_f32_e32 v8, v8, v27
	v_mul_f32_e32 v2, v2, v28
	v_mul_f32_e32 v4, v4, v29
	v_mul_f32_e32 v5, v5, v26
	v_mul_f32_e32 v19, v19, v27
	v_mul_f32_e32 v15, v15, v28
	v_mul_f32_e32 v17, v17, v29
	v_add_f32_e32 v5, v68, v5
	v_add_f32_e32 v19, v69, v19
	v_add_f32_e32 v15, v70, v15
	v_add_f32_e32 v17, v71, v17
	s_add_i32 s10, s10, -8
	v_add_u32_e32 v23, 8, v23
	s_cmp_eq_u32 s10, 0
	s_cbranch_scc0 .LBB0_1551
	s_movk_i32 s10, 0x104
	v_mad_i32_i24 v3, v9, s10, v21
	v_mov_b64_e32 v[12:13], s[0:1]
	v_mad_i64_i32 v[12:13], s[10:11], v3, s16, v[12:13]
	v_add_u32_e32 v0, s64, v0
	s_movk_i32 s10, 0xa27
	v_cmp_lt_i32_e64 s[40:41], s10, v0
	v_lshl_add_u64 v[10:11], v[10:11], 3, v[12:13]
	v_mov_b32_e32 v7, v5
	v_mov_b32_e32 v9, v19
	v_mov_b32_e32 v3, v15
	v_mov_b32_e32 v5, v17
	s_or_b64 s[8:9], s[40:41], s[8:9]
	global_store_dwordx4 v[10:11], v[6:9], off
	global_store_dwordx4 v[10:11], v[2:5], off offset:16
	s_andn2_b64 exec, exec, s[8:9]
	s_cbranch_execnz .LBB0_1550
